# adds: first memory-attention gate load issued before its barrier; dtype comment
# baseline (speedup 1.0000x reference)
.LBB0_402:
	v_sub_f32_e32 v17, v17, v15
	v_sub_f32_e32 v16, v16, v15
	v_exp_f32_e32 v68, v17
	v_exp_f32_e32 v17, v16
	v_sub_f32_e32 v16, v27, v15
	v_exp_f32_e32 v153, v16
	v_sub_f32_e32 v16, v26, v15
	v_exp_f32_e32 v151, v16
	v_sub_f32_e32 v16, v25, v15
	v_exp_f32_e32 v149, v16
	v_sub_f32_e32 v16, v24, v15
	v_exp_f32_e32 v147, v16
	v_sub_f32_e32 v16, v23, v15
	v_exp_f32_e32 v145, v16
	v_sub_f32_e32 v16, v22, v15
	v_sub_f32_e32 v7, v7, v15
	v_exp_f32_e32 v143, v16
	v_exp_f32_e32 v155, v7
	v_sub_f32_e32 v7, v19, v15
	v_exp_f32_e32 v135, v7
	v_sub_f32_e32 v7, v18, v15
	v_exp_f32_e32 v133, v7
	v_sub_f32_e32 v7, v9, v15
	v_sub_f32_e32 v16, v21, v15
	v_exp_f32_e32 v131, v7
	v_sub_f32_e32 v7, v8, v15
	v_exp_f32_e32 v141, v16
	v_sub_f32_e32 v16, v20, v15
	v_exp_f32_e32 v129, v7
	v_cvt_pk_bf16_f32 v34, v143, v145
	v_cvt_pk_bf16_f32 v35, v147, v149
	v_cvt_pk_bf16_f32 v36, v151, v153
	v_cvt_pk_bf16_f32 v37, v17, v68
	v_mov_b32_e32 v7, v1
	v_exp_f32_e32 v139, v16
	v_sub_f32_e32 v6, v6, v15
	v_add_u32_e32 v16, v93, v7
	v_add_u32_e32 v69, 0xd000, v16
	ds_read2_b64 v[18:21], v69 offset1:4
	v_exp_f32_e32 v137, v6
	ds_read2_b64 v[6:9], v69 offset0:8 offset1:12
	v_cvt_pk_bf16_f32 v62, v129, v131
	v_cvt_pk_bf16_f32 v63, v133, v135
	v_cvt_pk_bf16_f32 v64, v137, v155
	v_cvt_pk_bf16_f32 v65, v139, v141
	v_add_u32_e32 v15, 0xd800, v16
	v_add_f32_e32 v0, 0, v0
	s_waitcnt lgkmcnt(1)
	v_mfma_f32_16x16x32_bf16 v[2:5], v[18:21], v[62:65], v[2:5]
	ds_read2_b64 v[18:21], v15 offset0:32 offset1:36
	v_add_f32_e32 v0, v156, v0
	s_add_u32 s18, s40, s47
	s_waitcnt lgkmcnt(1)
	v_mfma_f32_16x16x32_bf16 v[30:33], v[6:9], v[34:37], v[2:5]
	v_mad_i64_i32 v[66:67], s[14:15], v90, s59, 0
	s_addc_u32 s19, s41, 0
	s_nop 0
	ds_read2_b64 v[2:5], v15 offset0:40 offset1:44
	v_add_u32_e32 v15, 0xe000, v16
	s_waitcnt lgkmcnt(1)
	v_mfma_f32_16x16x32_bf16 v[6:9], v[18:21], v[62:65], v[58:61]
	ds_read2_b64 v[18:21], v15 offset0:64 offset1:68
	v_mov_b32_e32 v93, v1
	v_readlane_b32 s6, v236, 9
	s_waitcnt lgkmcnt(1)
	v_mfma_f32_16x16x32_bf16 v[26:29], v[2:5], v[34:37], v[6:9]
	ds_read2_b64 v[2:5], v15 offset0:72 offset1:76
	v_add_u32_e32 v15, 0xe800, v16
	v_readlane_b32 s7, v236, 10
	s_waitcnt lgkmcnt(1)
	v_mfma_f32_16x16x32_bf16 v[6:9], v[18:21], v[62:65], v[54:57]
	ds_read2_b64 v[18:21], v15 offset0:96 offset1:100
	s_waitcnt lgkmcnt(1)
	v_mfma_f32_16x16x32_bf16 v[22:25], v[2:5], v[34:37], v[6:9]
	ds_read2_b64 v[2:5], v15 offset0:104 offset1:108
	v_add_u32_e32 v15, 0xf000, v16
	s_waitcnt lgkmcnt(1)
	v_mfma_f32_16x16x32_bf16 v[6:9], v[18:21], v[62:65], v[50:53]
	s_nop 2
	ds_read2_b64 v[50:53], v15 offset0:128 offset1:132
	s_waitcnt lgkmcnt(1)
	v_mfma_f32_16x16x32_bf16 v[18:21], v[2:5], v[34:37], v[6:9]
	ds_read2_b64 v[2:5], v15 offset0:136 offset1:140
	v_add_u32_e32 v15, 0xf800, v16
	s_waitcnt lgkmcnt(1)
	v_mfma_f32_16x16x32_bf16 v[6:9], v[50:53], v[62:65], v[46:49]
	s_nop 2
	ds_read2_b64 v[46:49], v15 offset0:160 offset1:164
	ds_read2_b64 v[50:53], v15 offset0:168 offset1:172
	v_add_u32_e32 v15, 0x3000, v69
	s_waitcnt lgkmcnt(2)
	v_mfma_f32_16x16x32_bf16 v[6:9], v[2:5], v[34:37], v[6:9]
	s_waitcnt lgkmcnt(1)
	v_mfma_f32_16x16x32_bf16 v[2:5], v[46:49], v[62:65], v[42:45]
	ds_read2_b64 v[46:49], v15 offset0:192 offset1:196
	ds_read2_b64 v[54:57], v15 offset0:200 offset1:204
	v_add_u32_e32 v15, 0x3800, v69
	v_lshl_add_u64 v[42:43], s[18:19], 0, v[66:67]
	s_waitcnt lgkmcnt(1)
	v_mfma_f32_16x16x32_bf16 v[38:41], v[46:49], v[62:65], v[38:41]
	v_add_f32_e64 v46, v110, v0
	v_add_f32_e64 v47, v111, v1
	v_lshl_add_u64 v[42:43], v[42:43], 0, v[92:93]
	v_pk_add_f32 v[46:47], v[112:113], v[46:47]
	v_mfma_f32_16x16x32_bf16 v[2:5], v[50:53], v[34:37], v[2:5]
	v_add_f32_e64 v46, v114, v46
	v_add_f32_e64 v47, v115, v47
	ds_read2_b64 v[50:53], v15 offset0:224 offset1:228
	ds_read2_b64 v[58:61], v15 offset0:232 offset1:236
	v_pk_add_f32 v[46:47], v[116:117], v[46:47]
	global_load_dwordx2 v[44:45], v[42:43], off nt
	s_waitcnt lgkmcnt(0)
	s_barrier
	v_pk_add_f32 v[46:47], v[118:119], v[46:47]
	v_mfma_f32_16x16x32_bf16 v[10:13], v[50:53], v[62:65], v[10:13]
	v_add_f32_e64 v46, v122, v46
	v_add_f32_e64 v47, v123, v47
	s_add_u32 s18, s42, s47
	v_pk_add_f32 v[46:47], v[94:95], v[46:47]
	v_mfma_f32_16x16x32_bf16 v[10:13], v[58:61], v[34:37], v[10:13]
	v_add_f32_e64 v46, v96, v46
	v_add_f32_e64 v47, v97, v47
	s_addc_u32 s19, s43, 0
	v_pk_add_f32 v[46:47], v[98:99], v[46:47]
	s_add_i32 s46, s46, s6
	v_pk_add_f32 v[46:47], v[100:101], v[46:47]
	s_add_i32 s45, s45, s35
	v_pk_add_f32 v[46:47], v[102:103], v[46:47]
	s_add_i32 s44, s44, s30
	v_pk_add_f32 v[46:47], v[104:105], v[46:47]
	s_cmpk_gt_i32 s46, 0xff
	v_pk_add_f32 v[46:47], v[106:107], v[46:47]
	s_waitcnt vmcnt(0)
	v_lshlrev_b32_e32 v49, 16, v44
	v_pk_add_f32 v[46:47], v[108:109], v[46:47]
	v_and_b32_e32 v44, 0xffff0000, v44
	v_pk_add_f32 v[46:47], v[120:121], v[46:47]
	s_nop 0
	v_add_f32_e32 v0, v47, v157
	v_fmac_f32_e32 v0, v46, v124
	v_mul_f32_e32 v16, v0, v126
	v_add_f32_e32 v0, 0, v127
	v_add_f32_e32 v0, v158, v0
	v_pk_add_f32 v[46:47], v[128:129], v[0:1]
	s_nop 0
	v_pk_add_f32 v[46:47], v[130:131], v[46:47]
	s_nop 0
	v_pk_add_f32 v[46:47], v[132:133], v[46:47]
	s_nop 0
	v_pk_add_f32 v[46:47], v[134:135], v[46:47]
	s_nop 0
	v_pk_add_f32 v[46:47], v[136:137], v[46:47]
	s_nop 0
	v_pk_add_f32 v[46:47], v[154:155], v[46:47]
	s_nop 0
	v_pk_add_f32 v[46:47], v[138:139], v[46:47]
	s_nop 0
	v_pk_add_f32 v[46:47], v[140:141], v[46:47]
	s_nop 0
	v_pk_add_f32 v[46:47], v[142:143], v[46:47]
	s_nop 0
	v_pk_add_f32 v[46:47], v[144:145], v[46:47]
	s_nop 0
	v_pk_add_f32 v[46:47], v[146:147], v[46:47]
	s_nop 0
	v_pk_add_f32 v[46:47], v[148:149], v[46:47]
	s_nop 0
	v_pk_add_f32 v[46:47], v[150:151], v[46:47]
	s_nop 0
	v_pk_add_f32 v[46:47], v[152:153], v[46:47]
	s_nop 0
	v_pk_add_f32 v[16:17], v[16:17], v[46:47]
	s_nop 0
	v_add_f32_e32 v0, v17, v68
	v_fmac_f32_e32 v0, v16, v14
	ds_bpermute_b32 v46, v91, v0
	v_mfma_f32_16x16x32_bf16 v[14:17], v[54:57], v[34:37], v[38:41]
	v_and_b32_e32 v54, 0xffff0000, v45
	v_ashrrev_i32_e32 v91, 31, v90
	s_waitcnt lgkmcnt(0)
	v_add_f32_e32 v0, v0, v46
	ds_bpermute_b32 v38, v125, v0
	v_mul_f32_e32 v40, 0xbfb8aa3b, v49
	v_mul_f32_e32 v41, 0xbfb8aa3b, v44
	v_exp_f32_e32 v40, v40
	v_exp_f32_e32 v41, v41
	s_waitcnt lgkmcnt(0)
	v_add_f32_e32 v0, v0, v38
	v_div_scale_f32 v38, s[14:15], v0, v0, 1.0
	v_rcp_f32_e32 v46, v38
	v_pk_add_f32 v[40:41], v[40:41], 1.0 op_sel_hi:[1,0]
	v_fma_f32 v34, -v38, v46, 1.0
	v_fmac_f32_e32 v46, v34, v46
	v_div_scale_f32 v34, vcc, 1.0, v0, 1.0
	v_mul_f32_e32 v47, v34, v46
	v_fma_f32 v35, -v38, v47, v34
	v_fmac_f32_e32 v47, v35, v46
	v_fma_f32 v48, -v38, v47, v34
	global_load_dwordx2 v[36:37], v[42:43], off offset:32 nt
	global_load_dwordx2 v[38:39], v[42:43], off offset:64 nt
	global_load_dwordx2 v[34:35], v[42:43], off offset:96 nt
	v_div_fmas_f32 v46, v48, v46, v47
	v_div_scale_f32 v48, s[14:15], v41, v41, v44
	v_rcp_f32_e32 v50, v48
	v_div_fixup_f32 v0, v46, v0, 1.0
	v_pk_mul_f32 v[30:31], v[30:31], v[0:1] op_sel_hi:[1,0]
	v_pk_mul_f32 v[32:33], v[32:33], v[0:1] op_sel_hi:[1,0]
	v_fma_f32 v51, -v48, v50, 1.0
	v_fmac_f32_e32 v50, v51, v50
	v_div_scale_f32 v51, vcc, v44, v41, v44
	v_mul_f32_e32 v52, v51, v50
	v_fma_f32 v53, -v48, v52, v51
	v_fmac_f32_e32 v52, v53, v50
	v_fma_f32 v48, -v48, v52, v51
	v_div_fmas_f32 v48, v48, v50, v52
	v_div_fixup_f32 v41, v48, v41, v44
	v_lshlrev_b32_e32 v52, 16, v45
	v_mul_f32_e32 v44, 0xbfb8aa3b, v52
	v_mul_f32_e32 v45, 0xbfb8aa3b, v54
	v_exp_f32_e32 v44, v44
	v_exp_f32_e32 v45, v45
	v_rcp_f32_e32 v48, v40
	s_nop 0
	v_mul_f32_e32 v40, v49, v48
	v_pk_add_f32 v[44:45], v[44:45], 1.0 op_sel_hi:[1,0]
	v_pk_mul_f32 v[30:31], v[30:31], v[40:41]
	v_lshlrev_b64 v[46:47], 12, v[90:91]
	v_lshl_add_u64 v[46:47], s[18:19], 0, v[46:47]
	v_pk_mul_f32 v[26:27], v[26:27], v[0:1] op_sel_hi:[1,0]
	v_rcp_f32_e32 v40, v45
	s_nop 0
	v_mul_f32_e32 v41, v54, v40
	v_rcp_f32_e32 v40, v44
	s_nop 0
	v_mul_f32_e32 v40, v52, v40
	v_pk_mul_f32 v[32:33], v[32:33], v[40:41]
	v_cvt_pk_bf16_f32 v40, v30, v31
	v_cvt_pk_bf16_f32 v41, v32, v33
	v_lshl_add_u64 v[30:31], v[46:47], 0, v[92:93]
	global_store_dwordx2 v[30:31], v[40:41], off
	v_pk_mul_f32 v[28:29], v[28:29], v[0:1] op_sel_hi:[1,0]
	v_pk_mul_f32 v[22:23], v[22:23], v[0:1] op_sel_hi:[1,0]
	v_pk_mul_f32 v[24:25], v[24:25], v[0:1] op_sel_hi:[1,0]
	v_pk_mul_f32 v[20:21], v[20:21], v[0:1] op_sel_hi:[1,0]
	v_pk_mul_f32 v[6:7], v[6:7], v[0:1] op_sel_hi:[1,0]
	v_pk_mul_f32 v[8:9], v[8:9], v[0:1] op_sel_hi:[1,0]
	s_waitcnt vmcnt(3)
	v_lshlrev_b32_e32 v48, 16, v36
	v_and_b32_e32 v36, 0xffff0000, v36
	v_mul_f32_e32 v44, 0xbfb8aa3b, v48
	v_mul_f32_e32 v45, 0xbfb8aa3b, v36
	v_exp_f32_e32 v44, v44
	v_exp_f32_e32 v45, v45
	v_and_b32_e32 v47, 0xffff0000, v37
	v_pk_mul_f32 v[2:3], v[2:3], v[0:1] op_sel_hi:[1,0]
	v_pk_mul_f32 v[4:5], v[4:5], v[0:1] op_sel_hi:[1,0]
	v_pk_add_f32 v[32:33], v[44:45], 1.0 op_sel_hi:[1,0]
	s_nop 0
	s_nop 0
	v_rcp_f32_e32 v40, v33
	s_nop 0
	v_mul_f32_e32 v33, v36, v40
	v_lshlrev_b32_e32 v45, 16, v37
	v_mul_f32_e32 v36, 0xbfb8aa3b, v45
	v_mul_f32_e32 v37, 0xbfb8aa3b, v47
	v_exp_f32_e32 v36, v36
	v_exp_f32_e32 v37, v37
	v_rcp_f32_e32 v40, v32
	s_nop 0
	v_mul_f32_e32 v32, v48, v40
	v_pk_add_f32 v[36:37], v[36:37], 1.0 op_sel_hi:[1,0]
	v_pk_mul_f32 v[26:27], v[26:27], v[32:33]
	v_cvt_pk_bf16_f32 v26, v26, v27
	v_rcp_f32_e32 v32, v37
	s_nop 0
	v_mul_f32_e32 v33, v47, v32
	s_waitcnt vmcnt(2)
	v_lshlrev_b32_e32 v37, 16, v38
	v_and_b32_e32 v38, 0xffff0000, v38
	v_mul_f32_e32 v40, 0xbfb8aa3b, v37
	v_mul_f32_e32 v41, 0xbfb8aa3b, v38
	v_exp_f32_e32 v40, v40
	v_exp_f32_e32 v41, v41
	v_rcp_f32_e32 v32, v36
	s_nop 0
	v_mul_f32_e32 v32, v45, v32
	v_pk_mul_f32 v[28:29], v[28:29], v[32:33]
	v_pk_add_f32 v[32:33], v[40:41], 1.0 op_sel_hi:[1,0]
	s_nop 0
	v_cvt_pk_bf16_f32 v27, v28, v29
	global_store_dwordx2 v[30:31], v[26:27], off offset:32
	v_rcp_f32_e32 v26, v33
	s_nop 0
	v_mul_f32_e32 v27, v38, v26
	v_lshlrev_b32_e32 v38, 16, v39
	v_and_b32_e32 v39, 0xffff0000, v39
	v_mul_f32_e32 v28, 0xbfb8aa3b, v38
	v_mul_f32_e32 v29, 0xbfb8aa3b, v39
	v_exp_f32_e32 v28, v28
	v_exp_f32_e32 v29, v29
	v_rcp_f32_e32 v26, v32
	s_nop 0
	v_mul_f32_e32 v26, v37, v26
	v_pk_add_f32 v[28:29], v[28:29], 1.0 op_sel_hi:[1,0]
	v_pk_mul_f32 v[26:27], v[22:23], v[26:27]
	s_waitcnt vmcnt(2)
	v_lshlrev_b32_e32 v37, 16, v34
	v_and_b32_e32 v34, 0xffff0000, v34
	v_cvt_pk_bf16_f32 v26, v26, v27
	v_rcp_f32_e32 v22, v29
	s_nop 0
	v_mul_f32_e32 v29, v39, v22
	global_load_dwordx2 v[22:23], v[42:43], off offset:128 nt
	v_mul_f32_e32 v32, 0xbfb8aa3b, v37
	v_mul_f32_e32 v33, 0xbfb8aa3b, v34
	v_exp_f32_e32 v32, v32
	v_exp_f32_e32 v33, v33
	v_rcp_f32_e32 v36, v28
	s_nop 0
	v_mul_f32_e32 v28, v38, v36
	v_pk_mul_f32 v[24:25], v[24:25], v[28:29]
	v_lshlrev_b32_e32 v36, 16, v35
	v_pk_add_f32 v[28:29], v[32:33], 1.0 op_sel_hi:[1,0]
	v_cvt_pk_bf16_f32 v27, v24, v25
	v_pk_mul_f32 v[24:25], v[18:19], v[0:1] op_sel_hi:[1,0]
	global_store_dwordx2 v[30:31], v[26:27], off offset:64
	v_rcp_f32_e32 v18, v29
	s_nop 0
	v_mul_f32_e32 v27, v34, v18
	v_and_b32_e32 v34, 0xffff0000, v35
	v_mul_f32_e32 v18, 0xbfb8aa3b, v36
	v_mul_f32_e32 v19, 0xbfb8aa3b, v34
	v_exp_f32_e32 v18, v18
	v_exp_f32_e32 v19, v19
	v_rcp_f32_e32 v26, v28
	s_nop 0
	v_mul_f32_e32 v26, v37, v26
	v_pk_add_f32 v[18:19], v[18:19], 1.0 op_sel_hi:[1,0]
	v_pk_mul_f32 v[24:25], v[24:25], v[26:27]
	s_waitcnt vmcnt(1)
	v_lshlrev_b32_e32 v38, 16, v22
	v_rcp_f32_e32 v26, v19
	s_nop 0
	v_mul_f32_e32 v19, v34, v26
	v_and_b32_e32 v22, 0xffff0000, v22
	global_load_dwordx2 v[26:27], v[42:43], off offset:160 nt
	global_load_dwordx2 v[28:29], v[42:43], off offset:192 nt
	global_load_dwordx2 v[32:33], v[42:43], off offset:224 nt
	v_mul_f32_e32 v34, 0xbfb8aa3b, v38
	v_mul_f32_e32 v35, 0xbfb8aa3b, v22
	v_exp_f32_e32 v34, v34
	v_exp_f32_e32 v35, v35
	v_rcp_f32_e32 v37, v18
	s_nop 0
	v_mul_f32_e32 v18, v36, v37
	v_pk_mul_f32 v[18:19], v[20:21], v[18:19]
	v_cvt_pk_bf16_f32 v20, v24, v25
	v_pk_add_f32 v[24:25], v[34:35], 1.0 op_sel_hi:[1,0]
	v_cvt_pk_bf16_f32 v21, v18, v19
	global_store_dwordx2 v[30:31], v[20:21], off offset:96
	v_rcp_f32_e32 v18, v25
	s_nop 0
	v_mul_f32_e32 v19, v22, v18
	v_lshlrev_b32_e32 v25, 16, v23
	v_and_b32_e32 v23, 0xffff0000, v23
	v_mul_f32_e32 v20, 0xbfb8aa3b, v25
	v_mul_f32_e32 v21, 0xbfb8aa3b, v23
	v_exp_f32_e32 v20, v20
	v_exp_f32_e32 v21, v21
	v_rcp_f32_e32 v18, v24
	s_nop 0
	v_mul_f32_e32 v18, v38, v18
	v_pk_add_f32 v[20:21], v[20:21], 1.0 op_sel_hi:[1,0]
	v_pk_mul_f32 v[6:7], v[6:7], v[18:19]
	v_cvt_pk_bf16_f32 v6, v6, v7
	v_rcp_f32_e32 v18, v21
	s_nop 0
	v_mul_f32_e32 v19, v23, v18
	v_rcp_f32_e32 v18, v20
	s_nop 0
	v_mul_f32_e32 v18, v25, v18
	v_pk_mul_f32 v[8:9], v[8:9], v[18:19]
	s_waitcnt vmcnt(3)
	v_lshlrev_b32_e32 v21, 16, v26
	v_and_b32_e32 v24, 0xffff0000, v26
	v_mul_f32_e32 v22, 0xbfb8aa3b, v21
	v_mul_f32_e32 v23, 0xbfb8aa3b, v24
	v_exp_f32_e32 v22, v22
	v_exp_f32_e32 v23, v23
	v_cvt_pk_bf16_f32 v7, v8, v9
	global_store_dwordx2 v[30:31], v[6:7], off offset:128
	v_pk_add_f32 v[18:19], v[22:23], 1.0 op_sel_hi:[1,0]
	s_nop 0
	s_nop 0
	v_rcp_f32_e32 v6, v19
	s_nop 0
	v_mul_f32_e32 v7, v24, v6
	v_lshlrev_b32_e32 v22, 16, v27
	v_and_b32_e32 v24, 0xffff0000, v27
	v_mul_f32_e32 v8, 0xbfb8aa3b, v22
	v_mul_f32_e32 v9, 0xbfb8aa3b, v24
	v_exp_f32_e32 v8, v8
	v_exp_f32_e32 v9, v9
	v_rcp_f32_e32 v6, v18
	s_nop 0
	v_mul_f32_e32 v6, v21, v6
	v_pk_add_f32 v[8:9], v[8:9], 1.0 op_sel_hi:[1,0]
	v_pk_mul_f32 v[2:3], v[2:3], v[6:7]
	v_cvt_pk_bf16_f32 v2, v2, v3
	v_rcp_f32_e32 v6, v9
	s_nop 0
	v_mul_f32_e32 v7, v24, v6
	s_waitcnt vmcnt(3)
	v_lshlrev_b32_e32 v20, 16, v28
	v_and_b32_e32 v9, 0xffff0000, v28
	v_mul_f32_e32 v18, 0xbfb8aa3b, v20
	v_mul_f32_e32 v19, 0xbfb8aa3b, v9
	v_exp_f32_e32 v18, v18
	v_exp_f32_e32 v19, v19
	v_rcp_f32_e32 v6, v8
	s_nop 0
	v_mul_f32_e32 v6, v22, v6
	v_pk_mul_f32 v[4:5], v[4:5], v[6:7]
	v_pk_add_f32 v[6:7], v[18:19], 1.0 op_sel_hi:[1,0]
	s_nop 0
	v_cvt_pk_bf16_f32 v3, v4, v5
	global_store_dwordx2 v[30:31], v[2:3], off offset:160
	v_pk_mul_f32 v[2:3], v[14:15], v[0:1] op_sel_hi:[1,0]
	v_rcp_f32_e32 v4, v7
	s_nop 0
	v_mul_f32_e32 v5, v9, v4
	v_lshlrev_b32_e32 v18, 16, v29
	v_and_b32_e32 v19, 0xffff0000, v29
	v_mul_f32_e32 v8, 0xbfb8aa3b, v18
	v_mul_f32_e32 v9, 0xbfb8aa3b, v19
	v_exp_f32_e32 v8, v8
	v_exp_f32_e32 v9, v9
	v_rcp_f32_e32 v4, v6
	s_nop 0
	v_mul_f32_e32 v4, v20, v4
	v_pk_add_f32 v[8:9], v[8:9], 1.0 op_sel_hi:[1,0]
	v_pk_mul_f32 v[2:3], v[2:3], v[4:5]
	v_pk_mul_f32 v[4:5], v[16:17], v[0:1] op_sel_hi:[1,0]
	v_cvt_pk_bf16_f32 v2, v2, v3
	v_rcp_f32_e32 v6, v9
	s_nop 0
	v_mul_f32_e32 v7, v19, v6
	s_waitcnt vmcnt(3)
	v_lshlrev_b32_e32 v16, 16, v32
	v_and_b32_e32 v9, 0xffff0000, v32
	v_mul_f32_e32 v14, 0xbfb8aa3b, v16
	v_mul_f32_e32 v15, 0xbfb8aa3b, v9
	v_exp_f32_e32 v14, v14
	v_exp_f32_e32 v15, v15
	v_rcp_f32_e32 v6, v8
	s_nop 0
	v_mul_f32_e32 v6, v18, v6
	v_pk_mul_f32 v[4:5], v[4:5], v[6:7]
	v_pk_add_f32 v[6:7], v[14:15], 1.0 op_sel_hi:[1,0]
	s_nop 0
	v_cvt_pk_bf16_f32 v3, v4, v5
	global_store_dwordx2 v[30:31], v[2:3], off offset:192
	v_pk_mul_f32 v[2:3], v[10:11], v[0:1] op_sel_hi:[1,0]
	v_rcp_f32_e32 v4, v7
	s_nop 0
	v_mul_f32_e32 v5, v9, v4
	v_lshlrev_b32_e32 v14, 16, v33
	v_and_b32_e32 v15, 0xffff0000, v33
	v_mul_f32_e32 v8, 0xbfb8aa3b, v14
	v_mul_f32_e32 v9, 0xbfb8aa3b, v15
	v_exp_f32_e32 v8, v8
	v_exp_f32_e32 v9, v9
	v_rcp_f32_e32 v4, v6
	s_nop 0
	v_mul_f32_e32 v4, v16, v4
	v_pk_add_f32 v[8:9], v[8:9], 1.0 op_sel_hi:[1,0]
	v_pk_mul_f32 v[2:3], v[2:3], v[4:5]
	v_pk_mul_f32 v[4:5], v[12:13], v[0:1] op_sel_hi:[1,0]
	v_cvt_pk_bf16_f32 v2, v2, v3
	v_rcp_f32_e32 v0, v9
	s_nop 0
	v_mul_f32_e32 v7, v15, v0
	v_rcp_f32_e32 v0, v8
	s_nop 0
	v_mul_f32_e32 v6, v14, v0
	v_pk_mul_f32 v[4:5], v[4:5], v[6:7]
	s_nop 0
	v_cvt_pk_bf16_f32 v3, v4, v5
	global_store_dwordx2 v[30:31], v[2:3], off offset:224
	s_cbranch_scc1 .LBB0_409
